# dilated chunk loop: the 16 v_pk_mul_f32 that rescale the output accumulators before the P.V MFMAs split into scalar v_mul_f32 pairs (bit-identical)
# baseline (speedup 1.0000x reference)
; #define LAS __attribute__((address_space(3)))
; __device__ __forceinline__ float fast_exp2(float x) { return __builtin_amdgcn_exp2f(x); }
; __device__ __forceinline__ int crow(int r, int hi) { return (r & 3) + 8 * (r >> 2) + 4 * hi; }
; __device__ __forceinline__ s16x4 vtr(const LAS char* p) { typedef short v4i16_t __attribute__((ext_vector_type(4))); return __builtin_bit_cast(s16x4, __builtin_amdgcn_ds_read_tr16_b64_v4i16((LAS v4i16_t*)p)); }
; __device__ __forceinline__ bf16x8 cat8(s16x4 a, s16x4 b) { return (bf16x8){a[0], a[1], a[2], a[3], b[0], b[1], b[2], b[3]}; }
; __device__ __forceinline__ bf16x8 packp(const f32x16& p, int b) { u32x4 w; w.x = cvt_pk_bf16(p[b], p[b + 1]); w.y = cvt_pk_bf16(p[b + 2], p[b + 3]); w.z = cvt_pk_bf16(p[b + 4], p[b + 5]); w.w = cvt_pk_bf16(p[b + 6], p[b + 7]); return __builtin_bit_cast(bf16x8, w); }
; __device__ __forceinline__ void dil_unit(int hs, int un, bf16_t* BIG, bf16_t* ZA, const float* __restrict__ BT, LAS char* lds) {
;     ...
;             f32x16 sc = {};
; #pragma unroll
;             for (int s = 0; s < 4; ++s) sc = __builtin_amdgcn_mfma_f32_32x32x16_bf16(ka[s], qf[s], sc, 0, 0, 0);
; #pragma unroll
;             for (int r = 0; r < 16; ++r) sc[r] += tg[160 - 32 * c + r32 - crow(r, hi)];
;             float rm = max16(sc); rm = fmaxf(rm, __shfl_xor(rm, 32));
;             const float mn = fmaxf(mrun, rm), alpha = fast_exp2(mrun - mn); mrun = mn;
;             float ps = 0.f;
; #pragma unroll
;             for (int r = 0; r < 16; ++r) { sc[r] = fast_exp2(sc[r] - mn); ps += sc[r]; }
;             l = l * alpha + ps; o0 *= alpha; o1 *= alpha;
;             const bf16x8 pb0 = packp(sc, 0), pb1 = packp(sc, 8);
; #pragma unroll
;             for (int i = 0; i < 4; ++i) *(LAS u32x4*)(vst + ((lane >> 3) + 8 * i) * VP + (lane & 7) * 16) = vv[i];
;             asm volatile("s_waitcnt lgkmcnt(0)" ::: "memory");
; #pragma unroll
;             for (int ks = 0; ks < 2; ++ks) { const bf16x8 pb = ks == 0 ? pb0 : pb1;
;                 const LAS char* vp = vst + va_off + ks * 16 * VP;
;                 const bf16x8 a0 = cat8(vtr(vp), vtr(vp + 8 * VP)), a1 = cat8(vtr(vp + 64), vtr(vp + 8 * VP + 64));
;                 o0 = __builtin_amdgcn_mfma_f32_32x32x16_bf16(a0, pb, o0, 0, 0, 0); o1 = __builtin_amdgcn_mfma_f32_32x32x16_bf16(a1, pb, o1, 0, 0, 0); }
;             asm volatile("s_waitcnt lgkmcnt(0)" ::: "memory");
.Ldil_nopf:
	ds_read2_b32 v[166:167], v93 offset0:26 offset1:27
	ds_read2_b32 v[168:169], v93 offset0:24 offset1:25
	ds_read2_b32 v[170:171], v93 offset0:18 offset1:19
	ds_read2_b32 v[172:173], v93 offset0:16 offset1:17
	ds_read2_b32 v[174:175], v93 offset0:10 offset1:11
	ds_read2_b32 v[188:189], v93 offset0:8 offset1:9
	ds_read2_b32 v[190:191], v93 offset0:2 offset1:3
	ds_read2_b32 v[192:193], v93 offset1:1
	v_mfma_f32_32x32x16_bf16 v[48:63], v[48:51], v[64:67], 0
	v_mfma_f32_32x32x16_bf16 v[48:63], v[110:113], v[68:71], v[48:63]
	v_mfma_f32_32x32x16_bf16 v[48:63], v[114:117], v[72:75], v[48:63]
	v_mfma_f32_32x32x16_bf16 v[48:63], v[118:121], v[76:79], v[48:63]
	s_waitcnt lgkmcnt(0)
	s_nop 10
	v_add_f32_e32 v0, v48, v167
	v_add_f32_e32 v48, v49, v166
	v_add_f32_e32 v49, v50, v169
	v_add_f32_e32 v50, v51, v168
	v_add_f32_e32 v51, v52, v171
	v_add_f32_e32 v52, v53, v170
	v_add_f32_e32 v53, v54, v173
	v_add_f32_e32 v54, v55, v172
	v_add_f32_e32 v55, v56, v175
	v_add_f32_e32 v56, v57, v174
	v_add_f32_e32 v57, v58, v189
	v_add_f32_e32 v58, v59, v188
	v_max_f32_e32 v110, v57, v58
	v_add_f32_e32 v59, v60, v191
	v_add_f32_e32 v60, v61, v190
	v_add_f32_e32 v15, v62, v193
	v_add_f32_e32 v61, v63, v192
	v_max_f32_e32 v111, v15, v61
	v_max_f32_e32 v14, v49, v50
	v_max_f32_e32 v62, v53, v54
	v_max_f32_e32 v63, v55, v56
	v_max3_f32 v111, v59, v60, v111
	v_max3_f32 v14, v0, v48, v14
	v_max3_f32 v62, v51, v52, v62
	v_max3_f32 v63, v63, v110, v111
	v_max3_f32 v14, v14, v62, v63
	v_mov_b32_e32 v62, v14
	s_nop 1
	v_permlane32_swap_b32_e32 v14, v62
	v_max3_f32 v14, v109, v14, v62
	v_sub_f32_e32 v0, v0, v14
	v_exp_f32_e32 v63, v0
	v_sub_f32_e32 v0, v48, v14
	v_sub_f32_e32 v62, v109, v14
	v_exp_f32_e32 v109, v0
	v_sub_f32_e32 v0, v49, v14
	v_exp_f32_e32 v110, v0
	v_sub_f32_e32 v0, v50, v14
	v_exp_f32_e32 v111, v0
	v_sub_f32_e32 v0, v51, v14
	v_exp_f32_e32 v112, v0
	v_sub_f32_e32 v0, v52, v14
	v_exp_f32_e32 v113, v0
	v_sub_f32_e32 v0, v53, v14
	v_exp_f32_e32 v114, v0
	v_sub_f32_e32 v0, v54, v14
	v_exp_f32_e32 v115, v0
	v_sub_f32_e32 v0, v55, v14
	v_exp_f32_e32 v116, v0
	v_sub_f32_e32 v0, v56, v14
	v_exp_f32_e32 v56, v0
	v_sub_f32_e32 v0, v57, v14
	v_exp_f32_e32 v57, v0
	v_sub_f32_e32 v0, v58, v14
	v_exp_f32_e32 v58, v0
	v_sub_f32_e32 v0, v59, v14
	v_exp_f32_e32 v59, v0
	v_sub_f32_e32 v0, v60, v14
	v_exp_f32_e32 v60, v0
	v_sub_f32_e32 v0, v15, v14
	v_exp_f32_e32 v15, v0
	v_sub_f32_e32 v0, v61, v14
	v_exp_f32_e32 v61, v0
	v_cvt_pk_bf16_f32 v52, v63, v109
	v_cvt_pk_bf16_f32 v53, v110, v111
	v_cvt_pk_bf16_f32 v54, v112, v113
	v_cvt_pk_bf16_f32 v55, v114, v115
	v_cvt_pk_bf16_f32 v48, v116, v56
	v_cvt_pk_bf16_f32 v49, v57, v58
	v_cvt_pk_bf16_f32 v50, v59, v60
	v_cvt_pk_bf16_f32 v51, v15, v61
	ds_write_b128 v104, v[2:5]
	ds_write_b128 v104, v[6:9] offset:1536
	ds_write_b128 v104, v[10:13] offset:3072
	ds_write_b128 v104, v[80:83] offset:4608
	v_add_f32_e32 v2, 0, v63
	v_add_f32_e32 v2, v109, v2
	v_add_f32_e32 v2, v110, v2
	v_add_f32_e32 v2, v111, v2
	v_add_f32_e32 v2, v112, v2
	v_add_f32_e32 v2, v113, v2
	v_add_f32_e32 v2, v114, v2
	v_add_f32_e32 v2, v115, v2
	v_add_f32_e32 v2, v116, v2
	v_add_f32_e32 v2, v56, v2
	v_add_f32_e32 v2, v57, v2
	v_add_f32_e32 v2, v58, v2
	v_add_f32_e32 v2, v59, v2
	v_add_f32_e32 v2, v60, v2
	v_add_f32_e32 v2, v15, v2
	s_waitcnt lgkmcnt(0)
	v_exp_f32_e32 v0, v62
	v_add_f32_e32 v10, v61, v2
	ds_read_b64_tr_b16 v[2:3], v105
	ds_read_b64_tr_b16 v[4:5], v105 offset:1536
	ds_read_b64_tr_b16 v[6:7], v105 offset:64
	ds_read_b64_tr_b16 v[8:9], v105 offset:1600
	v_mov_b32_e32 v109, v14
	v_mul_f32_e32 v46, v46, v0
	v_mul_f32_e32 v47, v47, v0
	v_mul_f32_e32 v44, v44, v0
	v_mul_f32_e32 v45, v45, v0
	v_mul_f32_e32 v42, v42, v0
	v_mul_f32_e32 v43, v43, v0
	v_mul_f32_e32 v40, v40, v0
	v_mul_f32_e32 v41, v41, v0
	v_mul_f32_e32 v38, v38, v0
	v_mul_f32_e32 v39, v39, v0
	v_mul_f32_e32 v36, v36, v0
	v_mul_f32_e32 v37, v37, v0
	v_mul_f32_e32 v34, v34, v0
	v_mul_f32_e32 v35, v35, v0
	v_mul_f32_e32 v32, v32, v0
	v_mul_f32_e32 v33, v33, v0
	v_mul_f32_e32 v30, v30, v0
	v_mul_f32_e32 v31, v31, v0
	v_mul_f32_e32 v28, v28, v0
	v_mul_f32_e32 v29, v29, v0
	v_mul_f32_e32 v26, v26, v0
	v_mul_f32_e32 v27, v27, v0
	v_mul_f32_e32 v24, v24, v0
	v_mul_f32_e32 v25, v25, v0
	v_mul_f32_e32 v22, v22, v0
	v_mul_f32_e32 v23, v23, v0
	v_mul_f32_e32 v20, v20, v0
	v_mul_f32_e32 v21, v21, v0
	v_mul_f32_e32 v18, v18, v0
	v_mul_f32_e32 v19, v19, v0
	v_mul_f32_e32 v16, v16, v0
	v_mul_f32_e32 v17, v17, v0
	s_waitcnt lgkmcnt(2)
	v_mfma_f32_32x32x16_bf16 v[32:47], v[2:5], v[52:55], v[32:47]
	v_fmac_f32_e32 v10, v108, v0
	v_mov_b32_e32 v108, v10
	s_waitcnt lgkmcnt(0)
	v_mfma_f32_32x32x16_bf16 v[16:31], v[6:9], v[52:55], v[16:31]
	ds_read_b64_tr_b16 v[2:3], v105 offset:3072
	ds_read_b64_tr_b16 v[4:5], v105 offset:4608
	ds_read_b64_tr_b16 v[6:7], v105 offset:3136
	ds_read_b64_tr_b16 v[8:9], v105 offset:4672
	s_waitcnt lgkmcnt(0)
	s_waitcnt lgkmcnt(2)
	v_mfma_f32_32x32x16_bf16 v[32:47], v[2:5], v[48:51], v[32:47]
	s_waitcnt lgkmcnt(0)
	v_mfma_f32_32x32x16_bf16 v[16:31], v[6:9], v[48:51], v[16:31]
	s_branch .LBB0_535
